# baseline (speedup 1.0000x reference)
; __device__ __forceinline__ void qkt8(f32x16& p0, f32x16& p1, const char* Ks, const i32x8* q8, int r32, int hi) {
;     const int s127 = 127, s124 = 124;
;     const int sw0 = (r32 >> 1) & 7, sw1 = ((32 + r32) >> 1) & 7; const char* rp0 = Ks + r32 * 128; const char* rp1 = Ks + (32 + r32) * 128;
;     ...
;     {   i32x8 ka = K8LD(rp0, 0, sw0), kb = K8LD(rp1, 0, sw1);
;         asm volatile("s_waitcnt lgkmcnt(0)" ::: "memory");
;         asm volatile("v_mfma_scale_f32_32x32x64_f8f6f4 %0, %1, %2, -4.0, %3, %4 op_sel_hi:[0,0,0]" : "=&v"(p0) : "v"(ka), "v"(q8[0]), "v"(s127), "v"(s124));
;         asm volatile("v_mfma_scale_f32_32x32x64_f8f6f4 %0, %1, %2, -4.0, %3, %4 op_sel_hi:[0,0,0]" : "=&v"(p1) : "v"(kb), "v"(q8[0]), "v"(s127), "v"(s124)); }
;     {   i32x8 ka = K8LD(rp0, 1, sw0), kb = K8LD(rp1, 1, sw1);
;         asm volatile("s_waitcnt lgkmcnt(0)" ::: "memory");
;         asm volatile("v_mfma_scale_f32_32x32x64_f8f6f4 %0, %1, %2, %0, %3, %4 op_sel_hi:[0,0,0]" : "+v"(p0) : "v"(ka), "v"(q8[1]), "v"(s127), "v"(s124));
;         asm volatile("v_mfma_scale_f32_32x32x64_f8f6f4 %0, %1, %2, %0, %3, %4 op_sel_hi:[0,0,0]" : "+v"(p1) : "v"(kb), "v"(q8[1]), "v"(s127), "v"(s124)); }
; }
; __device__ __forceinline__ void finishSM8(f32x16& p0, f32x16& p1, float& l_reg, i32x8& pa) {
;     for (int r = 0; r < 16; ++r) p1[r] = __builtin_amdgcn_exp2f(p1[r]);
;     float ps = 0; for (int r = 0; r < 16; ++r) ps += p0[r]; for (int r = 0; r < 16; ++r) ps += p1[r];
;     l_reg += ps;
; #pragma unroll
;     for (int q = 0; q < 4; ++q) { int v = 0; v = __builtin_amdgcn_cvt_pk_bf8_f32(p0[4 * q], p0[4 * q + 1], v, false); v = __builtin_amdgcn_cvt_pk_bf8_f32(p0[4 * q + 2], p0[4 * q + 3], v, true); pa[q] = v; }
; #pragma unroll
;     for (int q = 0; q < 4; ++q) { int v = 0; v = __builtin_amdgcn_cvt_pk_bf8_f32(p1[4 * q], p1[4 * q + 1], v, false); v = __builtin_amdgcn_cvt_pk_bf8_f32(p1[4 * q + 2], p1[4 * q + 3], v, true); pa[4 + q] = v; }
; }
; template <bool EXPQ>
; __device__ __forceinline__ void pv8(f32x16* o, const char* Vs, const i32x8& pa, int r32, int hi, f32x16& pe) {
;     const int s127 = 127; const char* vp = Vs + r32 * 80 + hi * 32;
;     {   const i32x8 v0 = *(const i32x8*)(vp), v1 = *(const i32x8*)(vp + 32 * 80);
;         asm volatile("s_waitcnt lgkmcnt(0)" ::: "memory");
.LBB0_1027:
	v_readfirstlane_b32 s98, v182
	v_readfirstlane_b32 s99, v183
	v_readfirstlane_b32 s100, v180
	v_readfirstlane_b32 s101, v181
	v_add_u32_e32 v250, v201, v202
	v_add_u32_e32 v251, v201, v203
	v_add_u32_e32 v252, v201, v205
	v_add_u32_e32 v253, v201, v206
	v_subrev_u32_e32 v184, s98, v182
	v_subrev_u32_e32 v186, s100, v180
	v_add_u32_e32 v250, 0xc000, v250
	v_add_u32_e32 v251, 0xc000, v251
	v_add_u32_e32 v252, 0xc000, v252
	v_add_u32_e32 v253, 0xc000, v253
	v_add_u32_e32 v185, 0x8000, v184
	v_add_u32_e32 v187, 0x8000, v186
	v_add_u32_e32 v180, 0xc000, v198
	v_add_u32_e32 v181, 0xc000, v200
	s_add_u32 s98, s98, s28
	s_addc_u32 s99, s99, s29
	s_add_u32 s98, s98, 0x49728000
	s_addc_u32 s99, s99, 0
	s_add_u32 s100, s100, s28
	s_addc_u32 s101, s101, s29
	s_add_u32 s100, s100, 0x48b28000
	s_addc_u32 s101, s101, 0
	s_nop 0
.Lfa_loop:
	ds_read_b128 v[208:211], v250 offset:16384
	ds_read_b128 v[212:215], v251 offset:16384
	ds_read_b128 v[216:219], v250 offset:20480
	ds_read_b128 v[220:223], v251 offset:20480
	ds_read_b128 v[224:227], v252 offset:16384
	ds_read_b128 v[228:231], v253 offset:16384
	ds_read_b128 v[232:235], v252 offset:20480
	ds_read_b128 v[236:239], v253 offset:20480
	ds_read_b128 v[136:139], v207
	ds_read_b128 v[140:143], v207 offset:16
	ds_read_b128 v[240:243], v207 offset:2560
	ds_read_b128 v[244:247], v207 offset:2576
	v_exp_f32_e32 v80, v80
	v_exp_f32_e32 v81, v81
	v_exp_f32_e32 v82, v82
	v_exp_f32_e32 v83, v83
	v_exp_f32_e32 v84, v84
	v_exp_f32_e32 v85, v85
	v_exp_f32_e32 v86, v86
	v_exp_f32_e32 v87, v87
	s_waitcnt lgkmcnt(8)
	v_mfma_scale_f32_32x32x64_f8f6f4 v[96:111], v[208:215], v[152:159], -4.0, v189, v190 op_sel_hi:[0,0,0]
	v_exp_f32_e32 v88, v88
	v_exp_f32_e32 v89, v89
	v_exp_f32_e32 v90, v90
	ds_read_b128 v[208:211], v207 offset:5120
	ds_read_b128 v[212:215], v207 offset:5136
	v_exp_f32_e32 v91, v91
	v_exp_f32_e32 v92, v92
	v_exp_f32_e32 v93, v93
	v_exp_f32_e32 v94, v94
	v_exp_f32_e32 v95, v95
	v_mfma_scale_f32_32x32x64_f8f6f4 v[112:127], v[216:223], v[152:159], -4.0, v189, v190 op_sel_hi:[0,0,0]
	v_cvt_pk_bf8_f32 v128, v64, v65
	v_cvt_pk_bf8_f32 v129, v68, v69
	v_cvt_pk_bf8_f32 v130, v72, v73
	v_cvt_pk_bf8_f32 v131, v76, v77
	ds_read_b128 v[216:219], v207 offset:7680
	ds_read_b128 v[220:223], v207 offset:7696
	v_add_f32_e32 v248, v64, v65
	v_cvt_pk_bf8_f32 v128, v66, v67 op_sel:[0,0,1]
	v_cvt_pk_bf8_f32 v129, v70, v71 op_sel:[0,0,1]
	v_cvt_pk_bf8_f32 v130, v74, v75 op_sel:[0,0,1]
	v_cvt_pk_bf8_f32 v131, v78, v79 op_sel:[0,0,1]
	v_add_f32_e32 v248, v66, v248
	v_add_f32_e32 v248, v67, v248
	v_add_f32_e32 v248, v68, v248
	v_add_f32_e32 v248, v69, v248
	v_add_f32_e32 v248, v70, v248
	s_waitcnt lgkmcnt(8)
	v_mfma_scale_f32_32x32x64_f8f6f4 v[96:111], v[224:231], v[144:151], v[96:111], v189, v190 op_sel_hi:[0,0,0]
	v_cvt_pk_bf8_f32 v132, v80, v81
	v_cvt_pk_bf8_f32 v133, v84, v85
	v_cvt_pk_bf8_f32 v134, v88, v89
	v_cvt_pk_bf8_f32 v135, v92, v93
	v_add_f32_e32 v249, v80, v81
	v_cvt_pk_bf8_f32 v132, v82, v83 op_sel:[0,0,1]
	v_cvt_pk_bf8_f32 v133, v86, v87 op_sel:[0,0,1]
	v_cvt_pk_bf8_f32 v134, v90, v91 op_sel:[0,0,1]
	v_cvt_pk_bf8_f32 v135, v94, v95 op_sel:[0,0,1]
	v_add_f32_e32 v248, v71, v248
	v_add_f32_e32 v248, v72, v248
	v_add_f32_e32 v248, v73, v248
	v_add_f32_e32 v248, v74, v248
	v_add_f32_e32 v248, v75, v248
	v_mfma_scale_f32_32x32x64_f8f6f4 v[112:127], v[232:239], v[144:151], v[112:127], v189, v190 op_sel_hi:[0,0,0]
	global_load_dwordx4 v[172:175], v184, s[98:99]
	global_load_dwordx4 v[168:171], v186, s[100:101]
	v_add_f32_e32 v248, v76, v248
	v_add_f32_e32 v248, v77, v248
	v_add_f32_e32 v249, v82, v249
	v_add_f32_e32 v248, v78, v248
	v_add_f32_e32 v249, v83, v249
	s_waitcnt lgkmcnt(4)
	v_mfma_f32_32x32x64_f8f6f4 v[0:15], v[128:135], v[136:143], v[0:15] cbsz:1
	v_add_f32_e32 v248, v79, v248
	v_add_f32_e32 v249, v84, v249
	v_add_f32_e32 v249, v85, v249
	v_add_f32_e32 v249, v86, v249
	v_add_f32_e32 v249, v87, v249
	v_add_f32_e32 v249, v88, v249
	v_add_f32_e32 v249, v89, v249
	v_add_f32_e32 v249, v90, v249
	v_add_f32_e32 v249, v91, v249
	v_add_f32_e32 v249, v92, v249
	v_mfma_f32_32x32x64_f8f6f4 v[16:31], v[128:135], v[240:247], v[16:31] cbsz:1
	v_add_f32_e32 v249, v93, v249
	v_add_f32_e32 v249, v94, v249
	v_add_f32_e32 v249, v95, v249
	v_add_f32_e32 v178, v178, v248
	v_exp_f32_e32 v96, v96
	v_exp_f32_e32 v97, v97
	v_exp_f32_e32 v98, v98
	v_exp_f32_e32 v99, v99
	v_add_f32_e32 v178, v178, v249
	s_waitcnt lgkmcnt(0)
	v_mfma_f32_32x32x64_f8f6f4 v[32:47], v[128:135], v[208:215], v[32:47] cbsz:1
	v_exp_f32_e32 v100, v100
	v_exp_f32_e32 v101, v101
	v_exp_f32_e32 v102, v102
	v_exp_f32_e32 v103, v103
	v_exp_f32_e32 v104, v104
	v_exp_f32_e32 v105, v105
	v_mfma_f32_32x32x64_f8f6f4 v[48:63], v[128:135], v[216:223], v[48:63] cbsz:1
	v_exp_f32_e32 v106, v106
	v_exp_f32_e32 v107, v107
	v_exp_f32_e32 v108, v108
	v_exp_f32_e32 v109, v109
	v_exp_f32_e32 v110, v110
	v_exp_f32_e32 v111, v111
	s_waitcnt vmcnt(2)
	ds_write_b128 v199, v[164:167] offset:32768
	ds_write_b64 v180, v[160:161] offset:32768
	ds_write_b64 v181, v[162:163] offset:32768
	s_waitcnt lgkmcnt(0)
	s_barrier
; __device__ __forceinline__ void qkt8(f32x16& p0, f32x16& p1, const char* Ks, const i32x8* q8, int r32, int hi) {
;     const int s127 = 127, s124 = 124;
;     const int sw0 = (r32 >> 1) & 7, sw1 = ((32 + r32) >> 1) & 7; const char* rp0 = Ks + r32 * 128; const char* rp1 = Ks + (32 + r32) * 128;
;     ...
;     {   i32x8 ka = K8LD(rp0, 0, sw0), kb = K8LD(rp1, 0, sw1);
;         asm volatile("s_waitcnt lgkmcnt(0)" ::: "memory");
;         asm volatile("v_mfma_scale_f32_32x32x64_f8f6f4 %0, %1, %2, -4.0, %3, %4 op_sel_hi:[0,0,0]" : "=&v"(p0) : "v"(ka), "v"(q8[0]), "v"(s127), "v"(s124));
;         asm volatile("v_mfma_scale_f32_32x32x64_f8f6f4 %0, %1, %2, -4.0, %3, %4 op_sel_hi:[0,0,0]" : "=&v"(p1) : "v"(kb), "v"(q8[0]), "v"(s127), "v"(s124)); }
;     {   i32x8 ka = K8LD(rp0, 1, sw0), kb = K8LD(rp1, 1, sw1);
;         asm volatile("s_waitcnt lgkmcnt(0)" ::: "memory");
;         asm volatile("v_mfma_scale_f32_32x32x64_f8f6f4 %0, %1, %2, %0, %3, %4 op_sel_hi:[0,0,0]" : "+v"(p0) : "v"(ka), "v"(q8[1]), "v"(s127), "v"(s124));
;         asm volatile("v_mfma_scale_f32_32x32x64_f8f6f4 %0, %1, %2, %0, %3, %4 op_sel_hi:[0,0,0]" : "+v"(p1) : "v"(kb), "v"(q8[1]), "v"(s127), "v"(s124)); }
; }
; __device__ __forceinline__ void finishSM8(f32x16& p0, f32x16& p1, float& l_reg, i32x8& pa) {
;     for (int r = 0; r < 16; ++r) p1[r] = __builtin_amdgcn_exp2f(p1[r]);
;     float ps = 0; for (int r = 0; r < 16; ++r) ps += p0[r]; for (int r = 0; r < 16; ++r) ps += p1[r];
;     l_reg += ps;
; #pragma unroll
;     for (int q = 0; q < 4; ++q) { int v = 0; v = __builtin_amdgcn_cvt_pk_bf8_f32(p0[4 * q], p0[4 * q + 1], v, false); v = __builtin_amdgcn_cvt_pk_bf8_f32(p0[4 * q + 2], p0[4 * q + 3], v, true); pa[q] = v; }
; #pragma unroll
;     for (int q = 0; q < 4; ++q) { int v = 0; v = __builtin_amdgcn_cvt_pk_bf8_f32(p1[4 * q], p1[4 * q + 1], v, false); v = __builtin_amdgcn_cvt_pk_bf8_f32(p1[4 * q + 2], p1[4 * q + 3], v, true); pa[4 + q] = v; }
; }
; template <bool EXPQ>
; __device__ __forceinline__ void pv8(f32x16* o, const char* Vs, const i32x8& pa, int r32, int hi, f32x16& pe) {
;     const int s127 = 127; const char* vp = Vs + r32 * 80 + hi * 32;
;     {   const i32x8 v0 = *(const i32x8*)(vp), v1 = *(const i32x8*)(vp + 32 * 80);
;         asm volatile("s_waitcnt lgkmcnt(0)" ::: "memory");
	ds_read_b128 v[208:211], v250 offset:32768
	ds_read_b128 v[212:215], v251 offset:32768
	ds_read_b128 v[216:219], v250 offset:36864
	ds_read_b128 v[220:223], v251 offset:36864
	ds_read_b128 v[224:227], v252 offset:32768
	ds_read_b128 v[228:231], v253 offset:32768
	ds_read_b128 v[232:235], v252 offset:36864
	ds_read_b128 v[236:239], v253 offset:36864
	ds_read_b128 v[136:139], v207 offset:16384
	ds_read_b128 v[140:143], v207 offset:16400
	ds_read_b128 v[240:243], v207 offset:18944
	ds_read_b128 v[244:247], v207 offset:18960
	v_exp_f32_e32 v112, v112
	v_exp_f32_e32 v113, v113
	v_exp_f32_e32 v114, v114
	v_exp_f32_e32 v115, v115
	v_exp_f32_e32 v116, v116
	v_exp_f32_e32 v117, v117
	v_exp_f32_e32 v118, v118
	v_exp_f32_e32 v119, v119
	s_waitcnt lgkmcnt(8)
	v_mfma_scale_f32_32x32x64_f8f6f4 v[64:79], v[208:215], v[152:159], -4.0, v189, v190 op_sel_hi:[0,0,0]
	v_exp_f32_e32 v120, v120
	v_exp_f32_e32 v121, v121
	v_exp_f32_e32 v122, v122
	ds_read_b128 v[208:211], v207 offset:21504
	ds_read_b128 v[212:215], v207 offset:21520
	v_exp_f32_e32 v123, v123
	v_exp_f32_e32 v124, v124
	v_exp_f32_e32 v125, v125
	v_exp_f32_e32 v126, v126
	v_exp_f32_e32 v127, v127
	v_mfma_scale_f32_32x32x64_f8f6f4 v[80:95], v[216:223], v[152:159], -4.0, v189, v190 op_sel_hi:[0,0,0]
	v_cvt_pk_bf8_f32 v128, v96, v97
	v_cvt_pk_bf8_f32 v129, v100, v101
	v_cvt_pk_bf8_f32 v130, v104, v105
	v_cvt_pk_bf8_f32 v131, v108, v109
	ds_read_b128 v[216:219], v207 offset:24064
	ds_read_b128 v[220:223], v207 offset:24080
	v_add_f32_e32 v248, v96, v97
	v_cvt_pk_bf8_f32 v128, v98, v99 op_sel:[0,0,1]
	v_cvt_pk_bf8_f32 v129, v102, v103 op_sel:[0,0,1]
	v_cvt_pk_bf8_f32 v130, v106, v107 op_sel:[0,0,1]
	v_cvt_pk_bf8_f32 v131, v110, v111 op_sel:[0,0,1]
	v_add_f32_e32 v248, v98, v248
	v_add_f32_e32 v248, v99, v248
	v_add_f32_e32 v248, v100, v248
	v_add_f32_e32 v248, v101, v248
	v_add_f32_e32 v248, v102, v248
	s_waitcnt lgkmcnt(8)
	v_mfma_scale_f32_32x32x64_f8f6f4 v[64:79], v[224:231], v[144:151], v[64:79], v189, v190 op_sel_hi:[0,0,0]
	v_cvt_pk_bf8_f32 v132, v112, v113
	v_cvt_pk_bf8_f32 v133, v116, v117
	v_cvt_pk_bf8_f32 v134, v120, v121
	v_cvt_pk_bf8_f32 v135, v124, v125
	v_add_f32_e32 v249, v112, v113
	v_cvt_pk_bf8_f32 v132, v114, v115 op_sel:[0,0,1]
	v_cvt_pk_bf8_f32 v133, v118, v119 op_sel:[0,0,1]
	v_cvt_pk_bf8_f32 v134, v122, v123 op_sel:[0,0,1]
	v_cvt_pk_bf8_f32 v135, v126, v127 op_sel:[0,0,1]
	v_add_f32_e32 v248, v103, v248
	v_add_f32_e32 v248, v104, v248
	v_add_f32_e32 v248, v105, v248
	v_add_f32_e32 v248, v106, v248
	v_add_f32_e32 v248, v107, v248
	v_mfma_scale_f32_32x32x64_f8f6f4 v[80:95], v[232:239], v[144:151], v[80:95], v189, v190 op_sel_hi:[0,0,0]
	s_cmp_ge_u32 s3, s69
	s_cbranch_scc1 .Lfa_skipse
	global_load_dwordx4 v[164:167], v185, s[98:99]
	global_load_dwordx4 v[160:163], v187, s[100:101]
.Lfa_skipse:
	s_add_u32 s98, s98, 0x10000
	s_addc_u32 s99, s99, 0
	s_add_u32 s100, s100, 0x10000
	s_addc_u32 s101, s101, 0
	v_add_f32_e32 v248, v108, v248
	v_add_f32_e32 v248, v109, v248
	v_add_f32_e32 v249, v114, v249
	v_add_f32_e32 v248, v110, v248
	v_add_f32_e32 v249, v115, v249
	s_waitcnt lgkmcnt(4)
	v_mfma_f32_32x32x64_f8f6f4 v[0:15], v[128:135], v[136:143], v[0:15] cbsz:1
	v_add_f32_e32 v248, v111, v248
	v_add_f32_e32 v249, v116, v249
	v_add_f32_e32 v249, v117, v249
	v_add_f32_e32 v249, v118, v249
	v_add_f32_e32 v249, v119, v249
	v_add_f32_e32 v249, v120, v249
	v_add_f32_e32 v249, v121, v249
	v_add_f32_e32 v249, v122, v249
	v_add_f32_e32 v249, v123, v249
	v_add_f32_e32 v249, v124, v249
	v_mfma_f32_32x32x64_f8f6f4 v[16:31], v[128:135], v[240:247], v[16:31] cbsz:1
	v_add_f32_e32 v249, v125, v249
	v_add_f32_e32 v249, v126, v249
	v_add_f32_e32 v249, v127, v249
	v_add_f32_e32 v178, v178, v248
	v_exp_f32_e32 v64, v64
	v_exp_f32_e32 v65, v65
	v_exp_f32_e32 v66, v66
	v_exp_f32_e32 v67, v67
	v_add_f32_e32 v178, v178, v249
	s_waitcnt lgkmcnt(0)
	v_mfma_f32_32x32x64_f8f6f4 v[32:47], v[128:135], v[208:215], v[32:47] cbsz:1
	v_exp_f32_e32 v68, v68
	v_exp_f32_e32 v69, v69
	v_exp_f32_e32 v70, v70
	v_exp_f32_e32 v71, v71
	v_exp_f32_e32 v72, v72
	v_exp_f32_e32 v73, v73
	v_mfma_f32_32x32x64_f8f6f4 v[48:63], v[128:135], v[216:223], v[48:63] cbsz:1
	v_exp_f32_e32 v74, v74
	v_exp_f32_e32 v75, v75
	v_exp_f32_e32 v76, v76
	v_exp_f32_e32 v77, v77
	v_exp_f32_e32 v78, v78
	v_exp_f32_e32 v79, v79
	s_cmp_ge_u32 s3, s69
	s_cbranch_scc1 .Lfa_last
	s_waitcnt vmcnt(2)
	ds_write_b128 v199, v[172:175]
	ds_write_b64 v180, v[168:169]
	ds_write_b64 v181, v[170:171]
	s_waitcnt lgkmcnt(0)
	s_barrier
; __device__ __forceinline__ void qkt8(f32x16& p0, f32x16& p1, const char* Ks, const i32x8* q8, int r32, int hi) {
;     const int s127 = 127, s124 = 124;
;     const int sw0 = (r32 >> 1) & 7, sw1 = ((32 + r32) >> 1) & 7; const char* rp0 = Ks + r32 * 128; const char* rp1 = Ks + (32 + r32) * 128;
;     ...
;     {   i32x8 ka = K8LD(rp0, 0, sw0), kb = K8LD(rp1, 0, sw1);
;         asm volatile("s_waitcnt lgkmcnt(0)" ::: "memory");
;         asm volatile("v_mfma_scale_f32_32x32x64_f8f6f4 %0, %1, %2, -4.0, %3, %4 op_sel_hi:[0,0,0]" : "=&v"(p0) : "v"(ka), "v"(q8[0]), "v"(s127), "v"(s124));
;         asm volatile("v_mfma_scale_f32_32x32x64_f8f6f4 %0, %1, %2, -4.0, %3, %4 op_sel_hi:[0,0,0]" : "=&v"(p1) : "v"(kb), "v"(q8[0]), "v"(s127), "v"(s124)); }
;     {   i32x8 ka = K8LD(rp0, 1, sw0), kb = K8LD(rp1, 1, sw1);
;         asm volatile("s_waitcnt lgkmcnt(0)" ::: "memory");
;         asm volatile("v_mfma_scale_f32_32x32x64_f8f6f4 %0, %1, %2, %0, %3, %4 op_sel_hi:[0,0,0]" : "+v"(p0) : "v"(ka), "v"(q8[1]), "v"(s127), "v"(s124));
;         asm volatile("v_mfma_scale_f32_32x32x64_f8f6f4 %0, %1, %2, %0, %3, %4 op_sel_hi:[0,0,0]" : "+v"(p1) : "v"(kb), "v"(q8[1]), "v"(s127), "v"(s124)); }
; }
; __device__ __forceinline__ void finishSM8(f32x16& p0, f32x16& p1, float& l_reg, i32x8& pa) {
;     for (int r = 0; r < 16; ++r) p1[r] = __builtin_amdgcn_exp2f(p1[r]);
;     float ps = 0; for (int r = 0; r < 16; ++r) ps += p0[r]; for (int r = 0; r < 16; ++r) ps += p1[r];
;     l_reg += ps;
; #pragma unroll
;     for (int q = 0; q < 4; ++q) { int v = 0; v = __builtin_amdgcn_cvt_pk_bf8_f32(p0[4 * q], p0[4 * q + 1], v, false); v = __builtin_amdgcn_cvt_pk_bf8_f32(p0[4 * q + 2], p0[4 * q + 3], v, true); pa[q] = v; }
; #pragma unroll
;     for (int q = 0; q < 4; ++q) { int v = 0; v = __builtin_amdgcn_cvt_pk_bf8_f32(p1[4 * q], p1[4 * q + 1], v, false); v = __builtin_amdgcn_cvt_pk_bf8_f32(p1[4 * q + 2], p1[4 * q + 3], v, true); pa[4 + q] = v; }
; }
; template <bool EXPQ>
; __device__ __forceinline__ void pv8(f32x16* o, const char* Vs, const i32x8& pa, int r32, int hi, f32x16& pe) {
;     const int s127 = 127; const char* vp = Vs + r32 * 80 + hi * 32;
;     {   const i32x8 v0 = *(const i32x8*)(vp), v1 = *(const i32x8*)(vp + 32 * 80);
;         asm volatile("s_waitcnt lgkmcnt(0)" ::: "memory");
	s_add_i32 s3, s3, 2
	ds_read_b128 v[208:211], v250
	ds_read_b128 v[212:215], v251
	ds_read_b128 v[216:219], v250 offset:4096
	ds_read_b128 v[220:223], v251 offset:4096
	ds_read_b128 v[224:227], v252
	ds_read_b128 v[228:231], v253
	ds_read_b128 v[232:235], v252 offset:4096
	ds_read_b128 v[236:239], v253 offset:4096
	ds_read_b128 v[136:139], v207 offset:32768
	ds_read_b128 v[140:143], v207 offset:32784
	ds_read_b128 v[240:243], v207 offset:35328
	ds_read_b128 v[244:247], v207 offset:35344
	v_exp_f32_e32 v80, v80
	v_exp_f32_e32 v81, v81
	v_exp_f32_e32 v82, v82
	v_exp_f32_e32 v83, v83
	v_exp_f32_e32 v84, v84
	v_exp_f32_e32 v85, v85
	v_exp_f32_e32 v86, v86
	v_exp_f32_e32 v87, v87
	s_waitcnt lgkmcnt(8)
	v_mfma_scale_f32_32x32x64_f8f6f4 v[96:111], v[208:215], v[152:159], -4.0, v189, v190 op_sel_hi:[0,0,0]
	v_exp_f32_e32 v88, v88
	v_exp_f32_e32 v89, v89
	v_exp_f32_e32 v90, v90
	ds_read_b128 v[208:211], v207 offset:37888
	ds_read_b128 v[212:215], v207 offset:37904
	v_exp_f32_e32 v91, v91
	v_exp_f32_e32 v92, v92
	v_exp_f32_e32 v93, v93
	v_exp_f32_e32 v94, v94
	v_exp_f32_e32 v95, v95
	v_mfma_scale_f32_32x32x64_f8f6f4 v[112:127], v[216:223], v[152:159], -4.0, v189, v190 op_sel_hi:[0,0,0]
	v_cvt_pk_bf8_f32 v128, v64, v65
	v_cvt_pk_bf8_f32 v129, v68, v69
	v_cvt_pk_bf8_f32 v130, v72, v73
	v_cvt_pk_bf8_f32 v131, v76, v77
	ds_read_b128 v[216:219], v207 offset:40448
	ds_read_b128 v[220:223], v207 offset:40464
	v_add_f32_e32 v248, v64, v65
	v_cvt_pk_bf8_f32 v128, v66, v67 op_sel:[0,0,1]
	v_cvt_pk_bf8_f32 v129, v70, v71 op_sel:[0,0,1]
	v_cvt_pk_bf8_f32 v130, v74, v75 op_sel:[0,0,1]
	v_cvt_pk_bf8_f32 v131, v78, v79 op_sel:[0,0,1]
	v_add_f32_e32 v248, v66, v248
	v_add_f32_e32 v248, v67, v248
	v_add_f32_e32 v248, v68, v248
	v_add_f32_e32 v248, v69, v248
	v_add_f32_e32 v248, v70, v248
	s_waitcnt lgkmcnt(8)
	v_mfma_scale_f32_32x32x64_f8f6f4 v[96:111], v[224:231], v[144:151], v[96:111], v189, v190 op_sel_hi:[0,0,0]
	v_cvt_pk_bf8_f32 v132, v80, v81
	v_cvt_pk_bf8_f32 v133, v84, v85
	v_cvt_pk_bf8_f32 v134, v88, v89
	v_cvt_pk_bf8_f32 v135, v92, v93
	v_add_f32_e32 v249, v80, v81
	v_cvt_pk_bf8_f32 v132, v82, v83 op_sel:[0,0,1]
	v_cvt_pk_bf8_f32 v133, v86, v87 op_sel:[0,0,1]
	v_cvt_pk_bf8_f32 v134, v90, v91 op_sel:[0,0,1]
	v_cvt_pk_bf8_f32 v135, v94, v95 op_sel:[0,0,1]
	v_add_f32_e32 v248, v71, v248
	v_add_f32_e32 v248, v72, v248
	v_add_f32_e32 v248, v73, v248
	v_add_f32_e32 v248, v74, v248
	v_add_f32_e32 v248, v75, v248
	v_mfma_scale_f32_32x32x64_f8f6f4 v[112:127], v[232:239], v[144:151], v[112:127], v189, v190 op_sel_hi:[0,0,0]
	global_load_dwordx4 v[172:175], v184, s[98:99]
	global_load_dwordx4 v[168:171], v186, s[100:101]
	v_add_f32_e32 v248, v76, v248
	v_add_f32_e32 v248, v77, v248
	v_add_f32_e32 v249, v82, v249
	v_add_f32_e32 v248, v78, v248
	v_add_f32_e32 v249, v83, v249
	s_waitcnt lgkmcnt(4)
	v_mfma_f32_32x32x64_f8f6f4 v[0:15], v[128:135], v[136:143], v[0:15] cbsz:1
	v_add_f32_e32 v248, v79, v248
	v_add_f32_e32 v249, v84, v249
	v_add_f32_e32 v249, v85, v249
	v_add_f32_e32 v249, v86, v249
	v_add_f32_e32 v249, v87, v249
	v_add_f32_e32 v249, v88, v249
	v_add_f32_e32 v249, v89, v249
	v_add_f32_e32 v249, v90, v249
	v_add_f32_e32 v249, v91, v249
	v_add_f32_e32 v249, v92, v249
	v_mfma_f32_32x32x64_f8f6f4 v[16:31], v[128:135], v[240:247], v[16:31] cbsz:1
	v_add_f32_e32 v249, v93, v249
	v_add_f32_e32 v249, v94, v249
	v_add_f32_e32 v249, v95, v249
	v_add_f32_e32 v178, v178, v248
	v_exp_f32_e32 v96, v96
	v_exp_f32_e32 v97, v97
	v_exp_f32_e32 v98, v98
	v_exp_f32_e32 v99, v99
	v_add_f32_e32 v178, v178, v249
	s_waitcnt lgkmcnt(0)
	v_mfma_f32_32x32x64_f8f6f4 v[32:47], v[128:135], v[208:215], v[32:47] cbsz:1
	v_exp_f32_e32 v100, v100
	v_exp_f32_e32 v101, v101
	v_exp_f32_e32 v102, v102
	v_exp_f32_e32 v103, v103
	v_exp_f32_e32 v104, v104
	v_exp_f32_e32 v105, v105
	v_mfma_f32_32x32x64_f8f6f4 v[48:63], v[128:135], v[216:223], v[48:63] cbsz:1
	v_exp_f32_e32 v106, v106
	v_exp_f32_e32 v107, v107
	v_exp_f32_e32 v108, v108
	v_exp_f32_e32 v109, v109
	v_exp_f32_e32 v110, v110
	v_exp_f32_e32 v111, v111
	s_waitcnt vmcnt(2)
	ds_write_b128 v199, v[164:167] offset:16384
	ds_write_b64 v180, v[160:161] offset:16384
	ds_write_b64 v181, v[162:163] offset:16384
	s_waitcnt lgkmcnt(0)
	s_barrier
	ds_read_b128 v[208:211], v250 offset:16384
	ds_read_b128 v[212:215], v251 offset:16384
	ds_read_b128 v[216:219], v250 offset:20480
	ds_read_b128 v[220:223], v251 offset:20480
	ds_read_b128 v[224:227], v252 offset:16384
	ds_read_b128 v[228:231], v253 offset:16384
	ds_read_b128 v[232:235], v252 offset:20480
	ds_read_b128 v[236:239], v253 offset:20480
	ds_read_b128 v[136:139], v207
	ds_read_b128 v[140:143], v207 offset:16
	ds_read_b128 v[240:243], v207 offset:2560
	ds_read_b128 v[244:247], v207 offset:2576
	v_exp_f32_e32 v112, v112
	v_exp_f32_e32 v113, v113
	v_exp_f32_e32 v114, v114
	v_exp_f32_e32 v115, v115
	v_exp_f32_e32 v116, v116
	v_exp_f32_e32 v117, v117
	v_exp_f32_e32 v118, v118
	v_exp_f32_e32 v119, v119
	s_waitcnt lgkmcnt(8)
	v_mfma_scale_f32_32x32x64_f8f6f4 v[64:79], v[208:215], v[152:159], -4.0, v189, v190 op_sel_hi:[0,0,0]
	v_exp_f32_e32 v120, v120
	v_exp_f32_e32 v121, v121
	v_exp_f32_e32 v122, v122
	ds_read_b128 v[208:211], v207 offset:5120
	ds_read_b128 v[212:215], v207 offset:5136
	v_exp_f32_e32 v123, v123
	v_exp_f32_e32 v124, v124
	v_exp_f32_e32 v125, v125
	v_exp_f32_e32 v126, v126
	v_exp_f32_e32 v127, v127
	v_mfma_scale_f32_32x32x64_f8f6f4 v[80:95], v[216:223], v[152:159], -4.0, v189, v190 op_sel_hi:[0,0,0]
	v_cvt_pk_bf8_f32 v128, v96, v97
	v_cvt_pk_bf8_f32 v129, v100, v101
	v_cvt_pk_bf8_f32 v130, v104, v105
	v_cvt_pk_bf8_f32 v131, v108, v109
	ds_read_b128 v[216:219], v207 offset:7680
	ds_read_b128 v[220:223], v207 offset:7696
	v_add_f32_e32 v248, v96, v97
	v_cvt_pk_bf8_f32 v128, v98, v99 op_sel:[0,0,1]
	v_cvt_pk_bf8_f32 v129, v102, v103 op_sel:[0,0,1]
	v_cvt_pk_bf8_f32 v130, v106, v107 op_sel:[0,0,1]
	v_cvt_pk_bf8_f32 v131, v110, v111 op_sel:[0,0,1]
	v_add_f32_e32 v248, v98, v248
	v_add_f32_e32 v248, v99, v248
	v_add_f32_e32 v248, v100, v248
	v_add_f32_e32 v248, v101, v248
	v_add_f32_e32 v248, v102, v248
	s_waitcnt lgkmcnt(8)
; __device__ __forceinline__ void qkt8(f32x16& p0, f32x16& p1, const char* Ks, const i32x8* q8, int r32, int hi) {
;     const int s127 = 127, s124 = 124;
;     const int sw0 = (r32 >> 1) & 7, sw1 = ((32 + r32) >> 1) & 7; const char* rp0 = Ks + r32 * 128; const char* rp1 = Ks + (32 + r32) * 128;
;     ...
;     {   i32x8 ka = K8LD(rp0, 0, sw0), kb = K8LD(rp1, 0, sw1);
;         asm volatile("s_waitcnt lgkmcnt(0)" ::: "memory");
;         asm volatile("v_mfma_scale_f32_32x32x64_f8f6f4 %0, %1, %2, -4.0, %3, %4 op_sel_hi:[0,0,0]" : "=&v"(p0) : "v"(ka), "v"(q8[0]), "v"(s127), "v"(s124));
;         asm volatile("v_mfma_scale_f32_32x32x64_f8f6f4 %0, %1, %2, -4.0, %3, %4 op_sel_hi:[0,0,0]" : "=&v"(p1) : "v"(kb), "v"(q8[0]), "v"(s127), "v"(s124)); }
;     {   i32x8 ka = K8LD(rp0, 1, sw0), kb = K8LD(rp1, 1, sw1);
;         asm volatile("s_waitcnt lgkmcnt(0)" ::: "memory");
;         asm volatile("v_mfma_scale_f32_32x32x64_f8f6f4 %0, %1, %2, %0, %3, %4 op_sel_hi:[0,0,0]" : "+v"(p0) : "v"(ka), "v"(q8[1]), "v"(s127), "v"(s124));
;         asm volatile("v_mfma_scale_f32_32x32x64_f8f6f4 %0, %1, %2, %0, %3, %4 op_sel_hi:[0,0,0]" : "+v"(p1) : "v"(kb), "v"(q8[1]), "v"(s127), "v"(s124)); }
; }
; __device__ __forceinline__ void finishSM8(f32x16& p0, f32x16& p1, float& l_reg, i32x8& pa) {
;     for (int r = 0; r < 16; ++r) p1[r] = __builtin_amdgcn_exp2f(p1[r]);
;     float ps = 0; for (int r = 0; r < 16; ++r) ps += p0[r]; for (int r = 0; r < 16; ++r) ps += p1[r];
;     l_reg += ps;
; #pragma unroll
;     for (int q = 0; q < 4; ++q) { int v = 0; v = __builtin_amdgcn_cvt_pk_bf8_f32(p0[4 * q], p0[4 * q + 1], v, false); v = __builtin_amdgcn_cvt_pk_bf8_f32(p0[4 * q + 2], p0[4 * q + 3], v, true); pa[q] = v; }
; #pragma unroll
;     for (int q = 0; q < 4; ++q) { int v = 0; v = __builtin_amdgcn_cvt_pk_bf8_f32(p1[4 * q], p1[4 * q + 1], v, false); v = __builtin_amdgcn_cvt_pk_bf8_f32(p1[4 * q + 2], p1[4 * q + 3], v, true); pa[4 + q] = v; }
; }
; template <bool EXPQ>
; __device__ __forceinline__ void pv8(f32x16* o, const char* Vs, const i32x8& pa, int r32, int hi, f32x16& pe) {
;     const int s127 = 127; const char* vp = Vs + r32 * 80 + hi * 32;
;     {   const i32x8 v0 = *(const i32x8*)(vp), v1 = *(const i32x8*)(vp + 32 * 80);
;         asm volatile("s_waitcnt lgkmcnt(0)" ::: "memory");
	v_mfma_scale_f32_32x32x64_f8f6f4 v[64:79], v[224:231], v[144:151], v[64:79], v189, v190 op_sel_hi:[0,0,0]
	v_cvt_pk_bf8_f32 v132, v112, v113
	v_cvt_pk_bf8_f32 v133, v116, v117
	v_cvt_pk_bf8_f32 v134, v120, v121
	v_cvt_pk_bf8_f32 v135, v124, v125
	v_add_f32_e32 v249, v112, v113
	v_cvt_pk_bf8_f32 v132, v114, v115 op_sel:[0,0,1]
	v_cvt_pk_bf8_f32 v133, v118, v119 op_sel:[0,0,1]
	v_cvt_pk_bf8_f32 v134, v122, v123 op_sel:[0,0,1]
	v_cvt_pk_bf8_f32 v135, v126, v127 op_sel:[0,0,1]
	v_add_f32_e32 v248, v103, v248
	v_add_f32_e32 v248, v104, v248
	v_add_f32_e32 v248, v105, v248
	v_add_f32_e32 v248, v106, v248
	v_add_f32_e32 v248, v107, v248
	v_mfma_scale_f32_32x32x64_f8f6f4 v[80:95], v[232:239], v[144:151], v[80:95], v189, v190 op_sel_hi:[0,0,0]
	global_load_dwordx4 v[164:167], v185, s[98:99]
	global_load_dwordx4 v[160:163], v187, s[100:101]
	s_add_u32 s98, s98, 0x10000
	s_addc_u32 s99, s99, 0
	s_add_u32 s100, s100, 0x10000
	s_addc_u32 s101, s101, 0
	v_add_f32_e32 v248, v108, v248
	v_add_f32_e32 v248, v109, v248
	v_add_f32_e32 v249, v114, v249
	v_add_f32_e32 v248, v110, v248
	v_add_f32_e32 v249, v115, v249
	s_waitcnt lgkmcnt(4)
	v_mfma_f32_32x32x64_f8f6f4 v[0:15], v[128:135], v[136:143], v[0:15] cbsz:1
	v_add_f32_e32 v248, v111, v248
	v_add_f32_e32 v249, v116, v249
	v_add_f32_e32 v249, v117, v249
	v_add_f32_e32 v249, v118, v249
	v_add_f32_e32 v249, v119, v249
	v_add_f32_e32 v249, v120, v249
	v_add_f32_e32 v249, v121, v249
	v_add_f32_e32 v249, v122, v249
	v_add_f32_e32 v249, v123, v249
	v_add_f32_e32 v249, v124, v249
	v_mfma_f32_32x32x64_f8f6f4 v[16:31], v[128:135], v[240:247], v[16:31] cbsz:1
	v_add_f32_e32 v249, v125, v249
	v_add_f32_e32 v249, v126, v249
	v_add_f32_e32 v249, v127, v249
	v_add_f32_e32 v178, v178, v248
	v_exp_f32_e32 v64, v64
	v_exp_f32_e32 v65, v65
	v_exp_f32_e32 v66, v66
	v_exp_f32_e32 v67, v67
	v_add_f32_e32 v178, v178, v249
	s_waitcnt lgkmcnt(0)
	v_mfma_f32_32x32x64_f8f6f4 v[32:47], v[128:135], v[208:215], v[32:47] cbsz:1
	v_exp_f32_e32 v68, v68
	v_exp_f32_e32 v69, v69
	v_exp_f32_e32 v70, v70
	v_exp_f32_e32 v71, v71
	v_exp_f32_e32 v72, v72
	v_exp_f32_e32 v73, v73
	v_mfma_f32_32x32x64_f8f6f4 v[48:63], v[128:135], v[216:223], v[48:63] cbsz:1
	v_exp_f32_e32 v74, v74
	v_exp_f32_e32 v75, v75
	v_exp_f32_e32 v76, v76
	v_exp_f32_e32 v77, v77
	v_exp_f32_e32 v78, v78
	v_exp_f32_e32 v79, v79
	s_waitcnt vmcnt(2)
	ds_write_b128 v199, v[172:175] offset:32768
	ds_write_b64 v180, v[168:169] offset:32768
	ds_write_b64 v181, v[170:171] offset:32768
	s_waitcnt lgkmcnt(0)
	s_barrier
	s_add_i32 s3, s3, 2
	ds_read_b128 v[208:211], v250 offset:32768
	ds_read_b128 v[212:215], v251 offset:32768
	ds_read_b128 v[216:219], v250 offset:36864
	ds_read_b128 v[220:223], v251 offset:36864
	ds_read_b128 v[224:227], v252 offset:32768
	ds_read_b128 v[228:231], v253 offset:32768
	ds_read_b128 v[232:235], v252 offset:36864
	ds_read_b128 v[236:239], v253 offset:36864
	ds_read_b128 v[136:139], v207 offset:16384
	ds_read_b128 v[140:143], v207 offset:16400
	ds_read_b128 v[240:243], v207 offset:18944
	ds_read_b128 v[244:247], v207 offset:18960
	v_exp_f32_e32 v80, v80
	v_exp_f32_e32 v81, v81
	v_exp_f32_e32 v82, v82
	v_exp_f32_e32 v83, v83
	v_exp_f32_e32 v84, v84
	v_exp_f32_e32 v85, v85
	v_exp_f32_e32 v86, v86
	v_exp_f32_e32 v87, v87
	s_waitcnt lgkmcnt(8)
	v_mfma_scale_f32_32x32x64_f8f6f4 v[96:111], v[208:215], v[152:159], -4.0, v189, v190 op_sel_hi:[0,0,0]
	v_exp_f32_e32 v88, v88
	v_exp_f32_e32 v89, v89
	v_exp_f32_e32 v90, v90
	ds_read_b128 v[208:211], v207 offset:21504
	ds_read_b128 v[212:215], v207 offset:21520
	v_exp_f32_e32 v91, v91
	v_exp_f32_e32 v92, v92
	v_exp_f32_e32 v93, v93
	v_exp_f32_e32 v94, v94
	v_exp_f32_e32 v95, v95
	v_mfma_scale_f32_32x32x64_f8f6f4 v[112:127], v[216:223], v[152:159], -4.0, v189, v190 op_sel_hi:[0,0,0]
	v_cvt_pk_bf8_f32 v128, v64, v65
	v_cvt_pk_bf8_f32 v129, v68, v69
	v_cvt_pk_bf8_f32 v130, v72, v73
	v_cvt_pk_bf8_f32 v131, v76, v77
	ds_read_b128 v[216:219], v207 offset:24064
	ds_read_b128 v[220:223], v207 offset:24080
	v_add_f32_e32 v248, v64, v65
	v_cvt_pk_bf8_f32 v128, v66, v67 op_sel:[0,0,1]
	v_cvt_pk_bf8_f32 v129, v70, v71 op_sel:[0,0,1]
	v_cvt_pk_bf8_f32 v130, v74, v75 op_sel:[0,0,1]
	v_cvt_pk_bf8_f32 v131, v78, v79 op_sel:[0,0,1]
	v_add_f32_e32 v248, v66, v248
	v_add_f32_e32 v248, v67, v248
	v_add_f32_e32 v248, v68, v248
	v_add_f32_e32 v248, v69, v248
	v_add_f32_e32 v248, v70, v248
	s_waitcnt lgkmcnt(8)
	v_mfma_scale_f32_32x32x64_f8f6f4 v[96:111], v[224:231], v[144:151], v[96:111], v189, v190 op_sel_hi:[0,0,0]
	v_cvt_pk_bf8_f32 v132, v80, v81
	v_cvt_pk_bf8_f32 v133, v84, v85
	v_cvt_pk_bf8_f32 v134, v88, v89
	v_cvt_pk_bf8_f32 v135, v92, v93
	v_add_f32_e32 v249, v80, v81
	v_cvt_pk_bf8_f32 v132, v82, v83 op_sel:[0,0,1]
	v_cvt_pk_bf8_f32 v133, v86, v87 op_sel:[0,0,1]
	v_cvt_pk_bf8_f32 v134, v90, v91 op_sel:[0,0,1]
	v_cvt_pk_bf8_f32 v135, v94, v95 op_sel:[0,0,1]
	v_add_f32_e32 v248, v71, v248
	v_add_f32_e32 v248, v72, v248
	v_add_f32_e32 v248, v73, v248
	v_add_f32_e32 v248, v74, v248
	v_add_f32_e32 v248, v75, v248
	v_mfma_scale_f32_32x32x64_f8f6f4 v[112:127], v[232:239], v[144:151], v[112:127], v189, v190 op_sel_hi:[0,0,0]
	global_load_dwordx4 v[172:175], v184, s[98:99]
	global_load_dwordx4 v[168:171], v186, s[100:101]
	v_add_f32_e32 v248, v76, v248
	v_add_f32_e32 v248, v77, v248
	v_add_f32_e32 v249, v82, v249
	v_add_f32_e32 v248, v78, v248
	v_add_f32_e32 v249, v83, v249
	s_waitcnt lgkmcnt(4)
	v_mfma_f32_32x32x64_f8f6f4 v[0:15], v[128:135], v[136:143], v[0:15] cbsz:1
	v_add_f32_e32 v248, v79, v248
	v_add_f32_e32 v249, v84, v249
	v_add_f32_e32 v249, v85, v249
	v_add_f32_e32 v249, v86, v249
	v_add_f32_e32 v249, v87, v249
	v_add_f32_e32 v249, v88, v249
	v_add_f32_e32 v249, v89, v249
	v_add_f32_e32 v249, v90, v249
	v_add_f32_e32 v249, v91, v249
	v_add_f32_e32 v249, v92, v249
	v_mfma_f32_32x32x64_f8f6f4 v[16:31], v[128:135], v[240:247], v[16:31] cbsz:1
	v_add_f32_e32 v249, v93, v249
	v_add_f32_e32 v249, v94, v249
	v_add_f32_e32 v249, v95, v249
	v_add_f32_e32 v178, v178, v248
	v_exp_f32_e32 v96, v96
	v_exp_f32_e32 v97, v97
	v_exp_f32_e32 v98, v98
	v_exp_f32_e32 v99, v99
	v_add_f32_e32 v178, v178, v249
	s_waitcnt lgkmcnt(0)
	v_mfma_f32_32x32x64_f8f6f4 v[32:47], v[128:135], v[208:215], v[32:47] cbsz:1
	v_exp_f32_e32 v100, v100
	v_exp_f32_e32 v101, v101
	v_exp_f32_e32 v102, v102
	v_exp_f32_e32 v103, v103
	v_exp_f32_e32 v104, v104
	v_exp_f32_e32 v105, v105
	v_mfma_f32_32x32x64_f8f6f4 v[48:63], v[128:135], v[216:223], v[48:63] cbsz:1
	v_exp_f32_e32 v106, v106
	v_exp_f32_e32 v107, v107
	v_exp_f32_e32 v108, v108
	v_exp_f32_e32 v109, v109
	v_exp_f32_e32 v110, v110
	v_exp_f32_e32 v111, v111
	s_waitcnt vmcnt(2)
	ds_write_b128 v199, v[164:167]
	ds_write_b64 v180, v[160:161]
	ds_write_b64 v181, v[162:163]
	s_waitcnt lgkmcnt(0)
	s_barrier
; __device__ __forceinline__ void qkt8(f32x16& p0, f32x16& p1, const char* Ks, const i32x8* q8, int r32, int hi) {
;     const int s127 = 127, s124 = 124;
;     const int sw0 = (r32 >> 1) & 7, sw1 = ((32 + r32) >> 1) & 7; const char* rp0 = Ks + r32 * 128; const char* rp1 = Ks + (32 + r32) * 128;
;     ...
;     {   i32x8 ka = K8LD(rp0, 0, sw0), kb = K8LD(rp1, 0, sw1);
;         asm volatile("s_waitcnt lgkmcnt(0)" ::: "memory");
;         asm volatile("v_mfma_scale_f32_32x32x64_f8f6f4 %0, %1, %2, -4.0, %3, %4 op_sel_hi:[0,0,0]" : "=&v"(p0) : "v"(ka), "v"(q8[0]), "v"(s127), "v"(s124));
;         asm volatile("v_mfma_scale_f32_32x32x64_f8f6f4 %0, %1, %2, -4.0, %3, %4 op_sel_hi:[0,0,0]" : "=&v"(p1) : "v"(kb), "v"(q8[0]), "v"(s127), "v"(s124)); }
;     {   i32x8 ka = K8LD(rp0, 1, sw0), kb = K8LD(rp1, 1, sw1);
;         asm volatile("s_waitcnt lgkmcnt(0)" ::: "memory");
;         asm volatile("v_mfma_scale_f32_32x32x64_f8f6f4 %0, %1, %2, %0, %3, %4 op_sel_hi:[0,0,0]" : "+v"(p0) : "v"(ka), "v"(q8[1]), "v"(s127), "v"(s124));
;         asm volatile("v_mfma_scale_f32_32x32x64_f8f6f4 %0, %1, %2, %0, %3, %4 op_sel_hi:[0,0,0]" : "+v"(p1) : "v"(kb), "v"(q8[1]), "v"(s127), "v"(s124)); }
; }
; __device__ __forceinline__ void finishSM8(f32x16& p0, f32x16& p1, float& l_reg, i32x8& pa) {
;     for (int r = 0; r < 16; ++r) p1[r] = __builtin_amdgcn_exp2f(p1[r]);
;     float ps = 0; for (int r = 0; r < 16; ++r) ps += p0[r]; for (int r = 0; r < 16; ++r) ps += p1[r];
;     l_reg += ps;
; #pragma unroll
;     for (int q = 0; q < 4; ++q) { int v = 0; v = __builtin_amdgcn_cvt_pk_bf8_f32(p0[4 * q], p0[4 * q + 1], v, false); v = __builtin_amdgcn_cvt_pk_bf8_f32(p0[4 * q + 2], p0[4 * q + 3], v, true); pa[q] = v; }
; #pragma unroll
;     for (int q = 0; q < 4; ++q) { int v = 0; v = __builtin_amdgcn_cvt_pk_bf8_f32(p1[4 * q], p1[4 * q + 1], v, false); v = __builtin_amdgcn_cvt_pk_bf8_f32(p1[4 * q + 2], p1[4 * q + 3], v, true); pa[4 + q] = v; }
; }
; template <bool EXPQ>
; __device__ __forceinline__ void pv8(f32x16* o, const char* Vs, const i32x8& pa, int r32, int hi, f32x16& pe) {
;     const int s127 = 127; const char* vp = Vs + r32 * 80 + hi * 32;
;     {   const i32x8 v0 = *(const i32x8*)(vp), v1 = *(const i32x8*)(vp + 32 * 80);
;         asm volatile("s_waitcnt lgkmcnt(0)" ::: "memory");
	ds_read_b128 v[208:211], v250
	ds_read_b128 v[212:215], v251
	ds_read_b128 v[216:219], v250 offset:4096
	ds_read_b128 v[220:223], v251 offset:4096
	ds_read_b128 v[224:227], v252
	ds_read_b128 v[228:231], v253
	ds_read_b128 v[232:235], v252 offset:4096
	ds_read_b128 v[236:239], v253 offset:4096
	ds_read_b128 v[136:139], v207 offset:32768
	ds_read_b128 v[140:143], v207 offset:32784
	ds_read_b128 v[240:243], v207 offset:35328
	ds_read_b128 v[244:247], v207 offset:35344
	v_exp_f32_e32 v112, v112
	v_exp_f32_e32 v113, v113
	v_exp_f32_e32 v114, v114
	v_exp_f32_e32 v115, v115
	v_exp_f32_e32 v116, v116
	v_exp_f32_e32 v117, v117
	v_exp_f32_e32 v118, v118
	v_exp_f32_e32 v119, v119
	s_waitcnt lgkmcnt(8)
	v_mfma_scale_f32_32x32x64_f8f6f4 v[64:79], v[208:215], v[152:159], -4.0, v189, v190 op_sel_hi:[0,0,0]
	v_exp_f32_e32 v120, v120
	v_exp_f32_e32 v121, v121
	v_exp_f32_e32 v122, v122
	ds_read_b128 v[208:211], v207 offset:37888
	ds_read_b128 v[212:215], v207 offset:37904
	v_exp_f32_e32 v123, v123
	v_exp_f32_e32 v124, v124
	v_exp_f32_e32 v125, v125
	v_exp_f32_e32 v126, v126
	v_exp_f32_e32 v127, v127
	v_mfma_scale_f32_32x32x64_f8f6f4 v[80:95], v[216:223], v[152:159], -4.0, v189, v190 op_sel_hi:[0,0,0]
	v_cvt_pk_bf8_f32 v128, v96, v97
	v_cvt_pk_bf8_f32 v129, v100, v101
	v_cvt_pk_bf8_f32 v130, v104, v105
	v_cvt_pk_bf8_f32 v131, v108, v109
	ds_read_b128 v[216:219], v207 offset:40448
	ds_read_b128 v[220:223], v207 offset:40464
	v_add_f32_e32 v248, v96, v97
	v_cvt_pk_bf8_f32 v128, v98, v99 op_sel:[0,0,1]
	v_cvt_pk_bf8_f32 v129, v102, v103 op_sel:[0,0,1]
	v_cvt_pk_bf8_f32 v130, v106, v107 op_sel:[0,0,1]
	v_cvt_pk_bf8_f32 v131, v110, v111 op_sel:[0,0,1]
	v_add_f32_e32 v248, v98, v248
	v_add_f32_e32 v248, v99, v248
	v_add_f32_e32 v248, v100, v248
	v_add_f32_e32 v248, v101, v248
	v_add_f32_e32 v248, v102, v248
	s_waitcnt lgkmcnt(8)
	v_mfma_scale_f32_32x32x64_f8f6f4 v[64:79], v[224:231], v[144:151], v[64:79], v189, v190 op_sel_hi:[0,0,0]
	v_cvt_pk_bf8_f32 v132, v112, v113
	v_cvt_pk_bf8_f32 v133, v116, v117
	v_cvt_pk_bf8_f32 v134, v120, v121
	v_cvt_pk_bf8_f32 v135, v124, v125
	v_add_f32_e32 v249, v112, v113
	v_cvt_pk_bf8_f32 v132, v114, v115 op_sel:[0,0,1]
	v_cvt_pk_bf8_f32 v133, v118, v119 op_sel:[0,0,1]
	v_cvt_pk_bf8_f32 v134, v122, v123 op_sel:[0,0,1]
	v_cvt_pk_bf8_f32 v135, v126, v127 op_sel:[0,0,1]
	v_add_f32_e32 v248, v103, v248
	v_add_f32_e32 v248, v104, v248
	v_add_f32_e32 v248, v105, v248
	v_add_f32_e32 v248, v106, v248
	v_add_f32_e32 v248, v107, v248
	v_mfma_scale_f32_32x32x64_f8f6f4 v[80:95], v[232:239], v[144:151], v[80:95], v189, v190 op_sel_hi:[0,0,0]
	global_load_dwordx4 v[164:167], v185, s[98:99]
	global_load_dwordx4 v[160:163], v187, s[100:101]
	s_add_u32 s98, s98, 0x10000
	s_addc_u32 s99, s99, 0
	s_add_u32 s100, s100, 0x10000
	s_addc_u32 s101, s101, 0
	v_add_f32_e32 v248, v108, v248
	v_add_f32_e32 v248, v109, v248
	v_add_f32_e32 v249, v114, v249
	v_add_f32_e32 v248, v110, v248
	v_add_f32_e32 v249, v115, v249
	s_waitcnt lgkmcnt(4)
	v_mfma_f32_32x32x64_f8f6f4 v[0:15], v[128:135], v[136:143], v[0:15] cbsz:1
	v_add_f32_e32 v248, v111, v248
	v_add_f32_e32 v249, v116, v249
	v_add_f32_e32 v249, v117, v249
	v_add_f32_e32 v249, v118, v249
	v_add_f32_e32 v249, v119, v249
	v_add_f32_e32 v249, v120, v249
	v_add_f32_e32 v249, v121, v249
	v_add_f32_e32 v249, v122, v249
	v_add_f32_e32 v249, v123, v249
	v_add_f32_e32 v249, v124, v249
	v_mfma_f32_32x32x64_f8f6f4 v[16:31], v[128:135], v[240:247], v[16:31] cbsz:1
	v_add_f32_e32 v249, v125, v249
	v_add_f32_e32 v249, v126, v249
	v_add_f32_e32 v249, v127, v249
	v_add_f32_e32 v178, v178, v248
	v_exp_f32_e32 v64, v64
	v_exp_f32_e32 v65, v65
	v_exp_f32_e32 v66, v66
	v_exp_f32_e32 v67, v67
	v_add_f32_e32 v178, v178, v249
	s_waitcnt lgkmcnt(0)
	v_mfma_f32_32x32x64_f8f6f4 v[32:47], v[128:135], v[208:215], v[32:47] cbsz:1
	v_exp_f32_e32 v68, v68
	v_exp_f32_e32 v69, v69
	v_exp_f32_e32 v70, v70
	v_exp_f32_e32 v71, v71
	v_exp_f32_e32 v72, v72
	v_exp_f32_e32 v73, v73
	v_mfma_f32_32x32x64_f8f6f4 v[48:63], v[128:135], v[216:223], v[48:63] cbsz:1
	v_exp_f32_e32 v74, v74
	v_exp_f32_e32 v75, v75
	v_exp_f32_e32 v76, v76
	v_exp_f32_e32 v77, v77
	v_exp_f32_e32 v78, v78
	v_exp_f32_e32 v79, v79
	s_waitcnt vmcnt(2)
	ds_write_b128 v199, v[172:175] offset:16384
	ds_write_b64 v180, v[168:169] offset:16384
	ds_write_b64 v181, v[170:171] offset:16384
	s_waitcnt lgkmcnt(0)
	s_barrier
	s_add_i32 s3, s3, 2
	s_branch .Lfa_loop
.Lfa_last:
	s_waitcnt vmcnt(0)
	ds_write_b128 v199, v[172:175]
	ds_write_b64 v180, v[168:169]
	ds_write_b64 v181, v[170:171]
	s_waitcnt lgkmcnt(0)
	s_barrier
	s_mov_b32 s48, 0x8000
	s_mov_b32 s49, 0

; __global__ void __launch_bounds__(512, 2) hymba_fwd(Params p) {
	.amdhsa_kernel _Z9hymba_fwd6Params
		.amdhsa_group_segment_fixed_size 0
		.amdhsa_private_segment_fixed_size 0
		.amdhsa_kernarg_size 448
		.amdhsa_user_sgpr_count 2
		.amdhsa_user_sgpr_dispatch_ptr 0
		.amdhsa_user_sgpr_queue_ptr 0
		.amdhsa_user_sgpr_kernarg_segment_ptr 1
		.amdhsa_user_sgpr_dispatch_id 0
		.amdhsa_user_sgpr_kernarg_preload_length 0
		.amdhsa_user_sgpr_kernarg_preload_offset 0
		.amdhsa_user_sgpr_private_segment_size 0
		.amdhsa_uses_dynamic_stack 0
		.amdhsa_enable_private_segment 0
		.amdhsa_system_sgpr_workgroup_id_x 1
		.amdhsa_system_sgpr_workgroup_id_y 0
		.amdhsa_system_sgpr_workgroup_id_z 0
		.amdhsa_system_sgpr_workgroup_info 0
		.amdhsa_system_vgpr_workitem_id 2
		.amdhsa_next_free_vgpr 255
		.amdhsa_next_free_sgpr 102
		.amdhsa_accum_offset 256
		.amdhsa_reserve_vcc 1
		.amdhsa_float_round_mode_32 0
		.amdhsa_float_round_mode_16_64 0
		.amdhsa_float_denorm_mode_32 3
		.amdhsa_float_denorm_mode_16_64 3
		.amdhsa_dx10_clamp 1
		.amdhsa_ieee_mode 1
		.amdhsa_fp16_overflow 0
		.amdhsa_tg_split 0
		.amdhsa_exception_fp_ieee_invalid_op 0
		.amdhsa_exception_fp_denorm_src 0
		.amdhsa_exception_fp_ieee_div_zero 0
		.amdhsa_exception_fp_ieee_overflow 0
		.amdhsa_exception_fp_ieee_underflow 0
		.amdhsa_exception_fp_ieee_inexact 0
		.amdhsa_exception_int_div_zero 0
	.end_amdhsa_kernel

; __global__ void __launch_bounds__(512, 2) hymba_fwd(Params p) {
amdhsa.kernels:
  - .agpr_count:     0
    .args:
      - .offset:         0
        .size:           192
        .value_kind:     by_value
      - .offset:         192
        .size:           4
        .value_kind:     hidden_block_count_x
      - .offset:         196
        .size:           4
        .value_kind:     hidden_block_count_y
      - .offset:         200
        .size:           4
        .value_kind:     hidden_block_count_z
      - .offset:         204
        .size:           2
        .value_kind:     hidden_group_size_x
      - .offset:         206
        .size:           2
        .value_kind:     hidden_group_size_y
      - .offset:         208
        .size:           2
        .value_kind:     hidden_group_size_z
      - .offset:         210
        .size:           2
        .value_kind:     hidden_remainder_x
      - .offset:         212
        .size:           2
        .value_kind:     hidden_remainder_y
      - .offset:         214
        .size:           2
        .value_kind:     hidden_remainder_z
      - .offset:         232
        .size:           8
        .value_kind:     hidden_global_offset_x
      - .offset:         240
        .size:           8
        .value_kind:     hidden_global_offset_y
      - .offset:         248
        .size:           8
        .value_kind:     hidden_global_offset_z
      - .offset:         256
        .size:           2
        .value_kind:     hidden_grid_dims
      - .offset:         280
        .size:           8
        .value_kind:     hidden_multigrid_sync_arg
      - .offset:         312
        .size:           4
        .value_kind:     hidden_dynamic_lds_size
    .group_segment_fixed_size: 0
    .kernarg_segment_align: 8
    .kernarg_segment_size: 448
    .language:       OpenCL C
    .language_version:
      - 2
      - 0
    .max_flat_workgroup_size: 512
    .name:           _Z9hymba_fwd6Params
    .private_segment_fixed_size: 0
    .sgpr_count:     108
    .sgpr_spill_count: 47
    .symbol:         _Z9hymba_fwd6Params.kd
    .uniform_work_group_size: 1
    .uses_dynamic_stack: false
    .vgpr_count:     255
    .vgpr_spill_count: 0
    .wavefront_size: 64
